# mLSTM walk compute segment: LDS operand reads for q.n, the output MFMAs and the state update batched up front with counted waits; shuffles overlapped with MFMAs
# speedup vs baseline: 1.0025x; 1.0025x over previous
.LBB0_541:
	s_or_b64 exec, exec, s[10:11]
	s_waitcnt lgkmcnt(0)
	s_barrier
	s_and_b64 vcc, exec, s[60:61]
	s_cbranch_vccnz .Lmlb_m0
	s_setprio 1
	ds_read_b96 v[54:56], v71 offset:46720
	v_and_b32_e32 v93, 32, v195
	v_mad_u32_u24 v93, v93, s34, v176
	ds_read_b128 v[46:49], v168
	ds_read_b128 v[66:69], v183 offset:46336
	ds_read_b128 v[112:115], v183 offset:46352
	ds_read_b128 v[50:53], v168 offset:16
	ds_read_b128 v[116:119], v183 offset:46368
	ds_read_b128 v[120:123], v183 offset:46384
	ds_read_b128 v[58:61], v168 offset:32
	ds_read_b128 v[136:139], v183 offset:46400
	ds_read_b128 v[140:143], v183 offset:46416
	ds_read_b128 v[246:249], v169
	ds_read_b128 v[198:201], v93 offset:31744
	ds_read_b128 v[202:205], v93 offset:35072
	ds_read_b128 v[250:253], v169 offset:64
	ds_read_b128 v[234:237], v93 offset:31808
	v_and_b32_e32 v144, 64, v209
	v_xor_b32_e32 v124, 1, v209
	v_add_u32_e32 v144, 64, v144
	v_cmp_lt_i32_e32 vcc, v124, v144
	s_nop 1
	v_cndmask_b32_e32 v124, v209, v124, vcc
	v_lshlrev_b32_e32 v124, 2, v124
	s_waitcnt lgkmcnt(11)
	v_lshlrev_b32_e32 v72, 16, v46
	v_and_b32_e32 v62, 0xffff0000, v46
	v_mul_f32_e32 v62, v67, v62
	v_fmac_f32_e32 v62, v66, v72
	v_lshlrev_b32_e32 v72, 16, v47
	v_fmac_f32_e32 v62, v68, v72
	v_and_b32_e32 v72, 0xffff0000, v47
	v_fmac_f32_e32 v62, v69, v72
	v_lshlrev_b32_e32 v72, 16, v48
	v_fmac_f32_e32 v62, v112, v72
	v_and_b32_e32 v72, 0xffff0000, v48
	v_fmac_f32_e32 v62, v113, v72
	v_lshlrev_b32_e32 v72, 16, v49
	v_fmac_f32_e32 v62, v114, v72
	v_and_b32_e32 v72, 0xffff0000, v49
	v_fmac_f32_e32 v62, v115, v72
	v_add_f32_e32 v73, 0, v62
	ds_read_b128 v[238:241], v93 offset:35136
	ds_read_b128 v[242:245], v169 offset:128
	ds_read_b128 v[66:69], v93 offset:31872
	ds_read_b128 v[112:115], v93 offset:35200
	s_waitcnt lgkmcnt(12)
	v_lshlrev_b32_e32 v72, 16, v50
	v_and_b32_e32 v63, 0xffff0000, v50
	v_mul_f32_e32 v63, v117, v63
	v_fmac_f32_e32 v63, v116, v72
	v_lshlrev_b32_e32 v72, 16, v51
	v_fmac_f32_e32 v63, v118, v72
	v_and_b32_e32 v72, 0xffff0000, v51
	v_fmac_f32_e32 v63, v119, v72
	v_lshlrev_b32_e32 v72, 16, v52
	v_fmac_f32_e32 v63, v120, v72
	v_and_b32_e32 v72, 0xffff0000, v52
	v_fmac_f32_e32 v63, v121, v72
	v_lshlrev_b32_e32 v72, 16, v53
	v_fmac_f32_e32 v63, v122, v72
	v_and_b32_e32 v72, 0xffff0000, v53
	v_fmac_f32_e32 v63, v123, v72
	v_add_f32_e32 v73, v73, v63
	s_waitcnt lgkmcnt(9)
	v_lshlrev_b32_e32 v72, 16, v58
	v_and_b32_e32 v70, 0xffff0000, v58
	v_mul_f32_e32 v70, v137, v70
	v_fmac_f32_e32 v70, v136, v72
	v_lshlrev_b32_e32 v72, 16, v59
	v_fmac_f32_e32 v70, v138, v72
	v_and_b32_e32 v72, 0xffff0000, v59
	v_fmac_f32_e32 v70, v139, v72
	v_lshlrev_b32_e32 v72, 16, v60
	v_fmac_f32_e32 v70, v140, v72
	v_and_b32_e32 v72, 0xffff0000, v60
	v_fmac_f32_e32 v70, v141, v72
	v_lshlrev_b32_e32 v72, 16, v61
	v_fmac_f32_e32 v70, v142, v72
	v_and_b32_e32 v72, 0xffff0000, v61
	v_fmac_f32_e32 v70, v143, v72
	v_add_f32_e32 v73, v73, v70
	ds_bpermute_b32 v132, v124, v73
	v_xor_b32_e32 v124, 2, v209
	v_cmp_lt_i32_e32 vcc, v124, v144
	s_nop 1
	v_cndmask_b32_e32 v124, v209, v124, vcc
	v_lshlrev_b32_e32 v124, 2, v124
	s_waitcnt lgkmcnt(7)
	v_mfma_f32_16x16x32_bf16 v[46:49], v[198:201], v[246:249], 0
	v_mfma_f32_16x16x32_bf16 v[50:53], v[202:205], v[246:249], 0
	ds_read_b64_tr_b16 v[58:59], v133 offset:26624
	ds_read_b64_tr_b16 v[60:61], v133 offset:26944
	ds_read_b64_tr_b16 v[116:117], v173 offset:13312
	ds_read_b64_tr_b16 v[118:119], v173 offset:14144
	s_waitcnt lgkmcnt(8)
	v_mfma_f32_16x16x32_bf16 v[46:49], v[234:237], v[250:253], v[46:49]
	v_mfma_f32_16x16x32_bf16 v[50:53], v[238:241], v[250:253], v[50:53]
	ds_read_b64_tr_b16 v[120:121], v134 offset:26624
	ds_read_b64_tr_b16 v[122:123], v134 offset:26944
	ds_read_b64_tr_b16 v[136:137], v174 offset:13312
	ds_read_b64_tr_b16 v[138:139], v174 offset:14144
	s_waitcnt lgkmcnt(9)
	v_mfma_f32_16x16x32_bf16 v[46:49], v[66:69], v[242:245], v[46:49]
	v_mfma_f32_16x16x32_bf16 v[50:53], v[112:115], v[242:245], v[50:53]
	s_waitcnt lgkmcnt(8)
	v_add_f32_e32 v73, v73, v132
	ds_bpermute_b32 v132, v124, v73
	ds_read_b64_tr_b16 v[140:141], v173 offset:13344
	ds_read_b64_tr_b16 v[142:143], v173 offset:14176
	ds_read_b64_tr_b16 v[198:199], v174 offset:13344
	ds_read_b64_tr_b16 v[200:201], v174 offset:14176
	v_add_u32_e32 v195, 32, v195
	v_and_b32_e32 v95, 32, v195
	v_mad_u32_u24 v95, v95, s34, v177
	s_waitcnt lgkmcnt(9)
	v_mfma_f32_16x16x32_bf16 v[116:119], v[58:61], v[116:119], 0
	s_waitcnt lgkmcnt(5)
	v_mfma_f32_16x16x32_bf16 v[116:119], v[120:123], v[136:139], v[116:119]
	s_waitcnt lgkmcnt(4)
	v_add_f32_e32 v73, v73, v132
	s_and_saveexec_b64 s[10:11], s[56:57]
	ds_write_b32 v184, v73 offset:46080
	s_or_b64 exec, exec, s[10:11]
	ds_read_b64_tr_b16 v[202:203], v173 offset:13376
	ds_read_b64_tr_b16 v[204:205], v173 offset:14208
	ds_read_b64_tr_b16 v[246:247], v174 offset:13376
	ds_read_b64_tr_b16 v[248:249], v174 offset:14208
	s_waitcnt lgkmcnt(7)
	v_mfma_f32_16x16x32_bf16 v[140:143], v[58:61], v[140:143], 0
	s_waitcnt lgkmcnt(5)
	v_mfma_f32_16x16x32_bf16 v[140:143], v[120:123], v[198:201], v[140:143]
	s_waitcnt lgkmcnt(2)
	v_mfma_f32_16x16x32_bf16 v[202:205], v[58:61], v[202:205], 0
	s_waitcnt lgkmcnt(0)
	v_mfma_f32_16x16x32_bf16 v[202:205], v[120:123], v[246:249], v[202:205]
	v_pk_mul_f32 v[116:117], v[56:57], v[116:117] op_sel_hi:[0,1]
	v_pk_mul_f32 v[118:119], v[56:57], v[118:119] op_sel_hi:[0,1]
	v_pk_fma_f32 v[10:11], v[10:11], v[54:55], v[116:117] op_sel_hi:[1,0,1]
	v_pk_fma_f32 v[12:13], v[12:13], v[54:55], v[118:119] op_sel_hi:[1,0,1]
	v_cvt_pk_bf16_f32 v135, v10, s0
	ds_write_b16 v95, v135 offset:31744
	v_cvt_pk_bf16_f32 v135, v11, s0
	ds_write_b16 v95, v135 offset:31952
	v_cvt_pk_bf16_f32 v135, v12, s0
	ds_write_b16 v95, v135 offset:32160
	v_cvt_pk_bf16_f32 v135, v13, s0
	ds_write_b16 v95, v135 offset:32368
	v_pk_mul_f32 v[140:141], v[56:57], v[140:141] op_sel_hi:[0,1]
	v_pk_mul_f32 v[142:143], v[56:57], v[142:143] op_sel_hi:[0,1]
	v_pk_fma_f32 v[6:7], v[6:7], v[54:55], v[140:141] op_sel_hi:[1,0,1]
	v_pk_fma_f32 v[8:9], v[8:9], v[54:55], v[142:143] op_sel_hi:[1,0,1]
	v_cvt_pk_bf16_f32 v135, v6, s0
	ds_write_b16 v95, v135 offset:31776
	v_cvt_pk_bf16_f32 v135, v7, s0
	ds_write_b16 v95, v135 offset:31984
	v_cvt_pk_bf16_f32 v135, v8, s0
	ds_write_b16 v95, v135 offset:32192
	v_cvt_pk_bf16_f32 v135, v9, s0
	ds_write_b16 v95, v135 offset:32400
	v_pk_mul_f32 v[202:203], v[56:57], v[202:203] op_sel_hi:[0,1]
	v_pk_mul_f32 v[204:205], v[56:57], v[204:205] op_sel_hi:[0,1]
	v_pk_fma_f32 v[2:3], v[2:3], v[54:55], v[202:203] op_sel_hi:[1,0,1]
	v_pk_fma_f32 v[4:5], v[4:5], v[54:55], v[204:205] op_sel_hi:[1,0,1]
	v_cvt_pk_bf16_f32 v135, v2, s0
	ds_write_b16 v95, v135 offset:31808
	v_cvt_pk_bf16_f32 v135, v3, s0
	ds_write_b16 v95, v135 offset:32016
	v_cvt_pk_bf16_f32 v135, v4, s0
	ds_write_b16 v95, v135 offset:32224
	v_cvt_pk_bf16_f32 v135, v5, s0
	ds_write_b16 v95, v135 offset:32432
	s_setprio 0
	s_branch .Lmlb_done
.Lmlb_m0:
	s_setprio 1
	ds_read_b96 v[54:56], v71 offset:46720
	ds_read_b64_tr_b16 v[58:59], v133 offset:26624
	ds_read_b64_tr_b16 v[60:61], v133 offset:26944
	ds_read_b64_tr_b16 v[116:117], v173 offset:13312
	ds_read_b64_tr_b16 v[118:119], v173 offset:14144
	ds_read_b64_tr_b16 v[120:121], v134 offset:26624
	ds_read_b64_tr_b16 v[122:123], v134 offset:26944
	ds_read_b64_tr_b16 v[136:137], v174 offset:13312
	ds_read_b64_tr_b16 v[138:139], v174 offset:14144
	ds_read_b64_tr_b16 v[140:141], v173 offset:13344
	ds_read_b64_tr_b16 v[142:143], v173 offset:14176
	ds_read_b64_tr_b16 v[198:199], v174 offset:13344
	ds_read_b64_tr_b16 v[200:201], v174 offset:14176
	ds_read_b64_tr_b16 v[202:203], v173 offset:13376
	ds_read_b64_tr_b16 v[204:205], v173 offset:14208
	v_add_u32_e32 v195, 32, v195
	v_and_b32_e32 v95, 32, v195
	v_mad_u32_u24 v95, v95, s34, v177
	s_waitcnt lgkmcnt(10)
	v_mfma_f32_16x16x32_bf16 v[116:119], v[58:61], v[116:119], 0
	ds_read_b64_tr_b16 v[246:247], v174 offset:13376
	ds_read_b64_tr_b16 v[248:249], v174 offset:14208
	s_waitcnt lgkmcnt(8)
	v_mfma_f32_16x16x32_bf16 v[116:119], v[120:123], v[136:139], v[116:119]
	s_waitcnt lgkmcnt(6)
	v_mfma_f32_16x16x32_bf16 v[140:143], v[58:61], v[140:143], 0
	s_waitcnt lgkmcnt(4)
	v_mfma_f32_16x16x32_bf16 v[140:143], v[120:123], v[198:201], v[140:143]
	s_waitcnt lgkmcnt(2)
	v_mfma_f32_16x16x32_bf16 v[202:205], v[58:61], v[202:205], 0
	s_waitcnt lgkmcnt(0)
	v_mfma_f32_16x16x32_bf16 v[202:205], v[120:123], v[246:249], v[202:205]
	s_nop 1
	v_pk_mul_f32 v[116:117], v[56:57], v[116:117] op_sel_hi:[0,1]
	v_pk_mul_f32 v[118:119], v[56:57], v[118:119] op_sel_hi:[0,1]
	v_pk_fma_f32 v[10:11], v[10:11], v[54:55], v[116:117] op_sel_hi:[1,0,1]
	v_pk_fma_f32 v[12:13], v[12:13], v[54:55], v[118:119] op_sel_hi:[1,0,1]
	v_cvt_pk_bf16_f32 v135, v10, s0
	ds_write_b16 v95, v135 offset:31744
	v_cvt_pk_bf16_f32 v135, v11, s0
	ds_write_b16 v95, v135 offset:31952
	v_cvt_pk_bf16_f32 v135, v12, s0
	ds_write_b16 v95, v135 offset:32160
	v_cvt_pk_bf16_f32 v135, v13, s0
	ds_write_b16 v95, v135 offset:32368
	v_pk_mul_f32 v[140:141], v[56:57], v[140:141] op_sel_hi:[0,1]
	v_pk_mul_f32 v[142:143], v[56:57], v[142:143] op_sel_hi:[0,1]
	v_pk_fma_f32 v[6:7], v[6:7], v[54:55], v[140:141] op_sel_hi:[1,0,1]
	v_pk_fma_f32 v[8:9], v[8:9], v[54:55], v[142:143] op_sel_hi:[1,0,1]
	v_cvt_pk_bf16_f32 v135, v6, s0
	ds_write_b16 v95, v135 offset:31776
	v_cvt_pk_bf16_f32 v135, v7, s0
	ds_write_b16 v95, v135 offset:31984
	v_cvt_pk_bf16_f32 v135, v8, s0
	ds_write_b16 v95, v135 offset:32192
	v_cvt_pk_bf16_f32 v135, v9, s0
	ds_write_b16 v95, v135 offset:32400
	v_pk_mul_f32 v[202:203], v[56:57], v[202:203] op_sel_hi:[0,1]
	v_pk_mul_f32 v[204:205], v[56:57], v[204:205] op_sel_hi:[0,1]
	v_pk_fma_f32 v[2:3], v[2:3], v[54:55], v[202:203] op_sel_hi:[1,0,1]
	v_pk_fma_f32 v[4:5], v[4:5], v[54:55], v[204:205] op_sel_hi:[1,0,1]
	v_cvt_pk_bf16_f32 v135, v2, s0
	ds_write_b16 v95, v135 offset:31808
	v_cvt_pk_bf16_f32 v135, v3, s0
	ds_write_b16 v95, v135 offset:32016
	v_cvt_pk_bf16_f32 v135, v4, s0
	ds_write_b16 v95, v135 offset:32224
	v_cvt_pk_bf16_f32 v135, v5, s0
	ds_write_b16 v95, v135 offset:32432
	s_setprio 0
.Lmlb_done:
	s_and_b64 vcc, exec, s[60:61]
	s_cbranch_vccz .LBB0_552
	s_and_saveexec_b64 s[10:11], s[50:51]
	s_cbranch_execnz .LBB0_553
